# attention: PV-phase priority kept through the phase's last two MFMAs (behind barrier 2)
# baseline (speedup 1.0000x reference)
.LqL_ldsb:
	s_add_i32 s33, s65, 0x10000
	s_and_b32 s33, s33, 0x18000
	s_add_i32 s33, s57, s33
	v_lshlrev_b32_e32 v198, 1, v150
	v_mfma_f32_32x32x16_bf16 v[32:47], v[242:245], v[64:67], v[32:47]
	s_mov_b32 m0, s33
	v_exp_f32_e32 v72, v72
	v_exp_f32_e32 v73, v73
	v_exp_f32_e32 v74, v74
	v_exp_f32_e32 v75, v75
	v_add_f32_e32 v184, v72, v73
	s_and_b32 s100, s65, 0x18000
	v_add_u32_e32 v194, s100, v149
	v_add_u32_e32 v195, v194, v157
	v_add_u32_e32 v196, v194, v193
	global_load_lds_dwordx4 v188, s[70:71]
	v_mfma_f32_32x32x16_bf16 v[48:63], v[246:249], v[64:67], v[48:63]
	v_exp_f32_e32 v76, v76
	v_exp_f32_e32 v77, v77
	v_cvt_pk_bf16_f32 v68, v72, v73
	v_add_f32_e32 v185, v74, v75
	v_cvt_pk_bf16_f32 v69, v74, v75
	v_add_u32_e32 v197, v194, v208
	v_add_u32_e32 v194, v194, v209
	ds_read_b128 v[132:135], v195
	ds_read_b128 v[116:119], v195 offset:4096
	v_mfma_f32_32x32x16_bf16 v[16:31], v[250:253], v[64:67], v[16:31]
	s_add_u32 s100, s70, 0x40000
	s_addc_u32 s101, s71, 0
	s_add_i32 m0, s33, 0x2000
	v_exp_f32_e32 v78, v78
	v_exp_f32_e32 v79, v79
	v_add_f32_e32 v186, v76, v77
	v_cvt_pk_bf16_f32 v70, v76, v77
	v_add_f32_e32 v184, v184, v185
	ds_read_b128 v[136:139], v196
	ds_read_b128 v[120:123], v196 offset:4096
	ds_read_b128 v[140:143], v197
	ds_read_b128 v[124:127], v197 offset:4096
	global_load_lds_dwordx4 v188, s[100:101]
	v_mfma_f32_32x32x16_bf16 v[0:15], v[200:203], v[64:67], v[0:15]
	v_add_f32_e32 v187, v78, v79
	v_cvt_pk_bf16_f32 v71, v78, v79
	v_add_f32_e32 v186, v186, v187
	v_add_f32_e32 v184, v184, v186
	v_add_f32_e32 v206, v206, v184
	ds_read_b128 v[128:131], v194
	ds_read_b128 v[112:115], v194 offset:4096
	ds_read_b128 v[242:245], v218 offset:16384
	ds_read_b128 v[246:249], v218 offset:20480
	ds_read_b128 v[250:253], v218 offset:24576
	ds_read_b128 v[200:203], v218 offset:28672
	v_mfma_f32_32x32x16_bf16 v[32:47], v[220:223], v[68:71], v[32:47]
	s_add_i32 m0, s33, 0x4000
	v_exp_f32_e32 v80, v80
	v_exp_f32_e32 v81, v81
	v_exp_f32_e32 v82, v82
	v_exp_f32_e32 v83, v83
	v_add_f32_e32 v184, v80, v81
	global_load_lds_dwordx4 v198, s[66:67]
	v_mfma_f32_32x32x16_bf16 v[48:63], v[224:227], v[68:71], v[48:63]
	v_exp_f32_e32 v84, v84
	v_exp_f32_e32 v85, v85
	v_cvt_pk_bf16_f32 v72, v80, v81
	v_add_f32_e32 v185, v82, v83
	v_cvt_pk_bf16_f32 v73, v82, v83
	v_mfma_f32_32x32x16_bf16 v[16:31], v[234:237], v[68:71], v[16:31]
	s_add_u32 s100, s66, 0x40000
	s_addc_u32 s101, s67, 0
	s_add_i32 m0, s33, 0x6000
	v_exp_f32_e32 v86, v86
	v_exp_f32_e32 v87, v87
	v_add_f32_e32 v186, v84, v85
	v_cvt_pk_bf16_f32 v74, v84, v85
	v_add_f32_e32 v184, v184, v185
	global_load_lds_dwordx4 v198, s[100:101]
	v_mfma_f32_32x32x16_bf16 v[0:15], v[238:241], v[68:71], v[0:15]
	v_add_f32_e32 v187, v86, v87
	v_cvt_pk_bf16_f32 v75, v86, v87
	v_add_f32_e32 v186, v186, v187
	v_add_f32_e32 v184, v184, v186
	v_add_f32_e32 v206, v206, v184
	ds_read_b128 v[220:223], v219 offset:16384
	ds_read_b128 v[224:227], v219 offset:20480
	ds_read_b128 v[234:237], v219 offset:24576
	ds_read_b128 v[238:241], v219 offset:28672
	s_waitcnt lgkmcnt(4)
	v_mfma_f32_32x32x16_bf16 v[32:47], v[242:245], v[72:75], v[32:47]
	s_add_u32 s100, s70, 0x1000
	s_addc_u32 s101, s71, 0
	s_add_i32 m0, s33, 0x1000
	v_exp_f32_e32 v88, v88
	v_exp_f32_e32 v89, v89
	v_exp_f32_e32 v90, v90
	v_exp_f32_e32 v91, v91
	v_add_f32_e32 v184, v88, v89
	global_load_lds_dwordx4 v188, s[100:101]
	v_mfma_f32_32x32x16_bf16 v[48:63], v[246:249], v[72:75], v[48:63]
	v_exp_f32_e32 v92, v92
	v_exp_f32_e32 v93, v93
	v_cvt_pk_bf16_f32 v76, v88, v89
	v_add_f32_e32 v185, v90, v91
	v_cvt_pk_bf16_f32 v77, v90, v91
	v_mfma_f32_32x32x16_bf16 v[16:31], v[250:253], v[72:75], v[16:31]
	s_add_u32 s100, s70, 0x41000
	s_addc_u32 s101, s71, 0
	s_add_i32 m0, s33, 0x3000
	v_exp_f32_e32 v94, v94
	v_exp_f32_e32 v95, v95
	v_add_f32_e32 v186, v92, v93
	v_cvt_pk_bf16_f32 v78, v92, v93
	v_add_f32_e32 v184, v184, v185
	global_load_lds_dwordx4 v188, s[100:101]
	v_mfma_f32_32x32x16_bf16 v[0:15], v[200:203], v[72:75], v[0:15]
	v_add_f32_e32 v187, v94, v95
	v_cvt_pk_bf16_f32 v79, v94, v95
	v_add_f32_e32 v186, v186, v187
	v_add_f32_e32 v184, v184, v186
	v_add_f32_e32 v206, v206, v184
	s_waitcnt lgkmcnt(0)
	v_mfma_f32_32x32x16_bf16 v[32:47], v[220:223], v[76:79], v[32:47]
	s_add_u32 s100, s66, 0x20000
	s_addc_u32 s101, s67, 0
	s_add_i32 m0, s33, 0x5000
	s_nop 0
	global_load_lds_dwordx4 v198, s[100:101]
	v_mfma_f32_32x32x16_bf16 v[48:63], v[224:227], v[76:79], v[48:63]
	s_add_u32 s100, s66, 0x60000
	s_addc_u32 s101, s67, 0
	s_add_i32 m0, s33, 0x7000
	s_nop 0
	global_load_lds_dwordx4 v198, s[100:101]
	s_waitcnt lgkmcnt(0)
	s_barrier
	s_add_i32 s65, s65, 0x8000
	s_addk_i32 s23, 0x100
	s_add_i32 s36, s36, 64
	s_mov_b32 s33, s54
	s_cmpk_eq_i32 s23, 0x1e00
	v_mfma_f32_32x32x16_bf16 v[16:31], v[234:237], v[76:79], v[16:31]
	v_mfma_f32_32x32x16_bf16 v[0:15], v[238:241], v[76:79], v[0:15]
	s_setprio 0
	s_cbranch_scc0 .LqL_top
	s_branch .LBB0_284

.LqT_g0:
	v_exp_f32_e32 v64, v64
	v_exp_f32_e32 v65, v65
	v_exp_f32_e32 v66, v66
	v_exp_f32_e32 v67, v67
	v_add_f32_e32 v184, v64, v65
	v_exp_f32_e32 v68, v68
	v_exp_f32_e32 v69, v69
	v_cvt_pk_bf16_f32 v64, v64, v65
	v_add_f32_e32 v185, v66, v67
	v_cvt_pk_bf16_f32 v65, v66, v67
	v_exp_f32_e32 v70, v70
	v_exp_f32_e32 v71, v71
	v_add_f32_e32 v186, v68, v69
	v_cvt_pk_bf16_f32 v66, v68, v69
	v_add_f32_e32 v184, v184, v185
	v_add_f32_e32 v187, v70, v71
	v_cvt_pk_bf16_f32 v67, v70, v71
	v_add_f32_e32 v186, v186, v187
	v_add_f32_e32 v184, v184, v186
	v_add_f32_e32 v206, v206, v184
	s_waitcnt vmcnt(0) lgkmcnt(0)
	s_barrier
	s_add_i32 s54, s33, 1
	s_setprio 1
	v_mfma_f32_32x32x16_bf16 v[32:47], v[242:245], v[64:67], v[32:47]
	v_exp_f32_e32 v72, v72
	v_exp_f32_e32 v73, v73
	v_exp_f32_e32 v74, v74
	v_exp_f32_e32 v75, v75
	v_add_f32_e32 v184, v72, v73
	s_and_b32 s100, s65, 0x18000
	v_add_u32_e32 v194, s100, v149
	v_add_u32_e32 v195, v194, v157
	v_add_u32_e32 v196, v194, v193
	v_mfma_f32_32x32x16_bf16 v[48:63], v[246:249], v[64:67], v[48:63]
	v_exp_f32_e32 v76, v76
	v_exp_f32_e32 v77, v77
	v_cvt_pk_bf16_f32 v68, v72, v73
	v_add_f32_e32 v185, v74, v75
	v_cvt_pk_bf16_f32 v69, v74, v75
	v_add_u32_e32 v197, v194, v208
	v_add_u32_e32 v194, v194, v209
	ds_read_b128 v[132:135], v195
	ds_read_b128 v[116:119], v195 offset:4096
	v_mfma_f32_32x32x16_bf16 v[16:31], v[250:253], v[64:67], v[16:31]
	v_exp_f32_e32 v78, v78
	v_exp_f32_e32 v79, v79
	v_add_f32_e32 v186, v76, v77
	v_cvt_pk_bf16_f32 v70, v76, v77
	v_add_f32_e32 v184, v184, v185
	ds_read_b128 v[136:139], v196
	ds_read_b128 v[120:123], v196 offset:4096
	ds_read_b128 v[140:143], v197
	ds_read_b128 v[124:127], v197 offset:4096
	v_mfma_f32_32x32x16_bf16 v[0:15], v[200:203], v[64:67], v[0:15]
	v_add_f32_e32 v187, v78, v79
	v_cvt_pk_bf16_f32 v71, v78, v79
	v_add_f32_e32 v186, v186, v187
	v_add_f32_e32 v184, v184, v186
	v_add_f32_e32 v206, v206, v184
	ds_read_b128 v[128:131], v194
	ds_read_b128 v[112:115], v194 offset:4096
	ds_read_b128 v[242:245], v218 offset:16384
	ds_read_b128 v[246:249], v218 offset:20480
	ds_read_b128 v[250:253], v218 offset:24576
	ds_read_b128 v[200:203], v218 offset:28672
	v_mfma_f32_32x32x16_bf16 v[32:47], v[220:223], v[68:71], v[32:47]
	v_exp_f32_e32 v80, v80
	v_exp_f32_e32 v81, v81
	v_exp_f32_e32 v82, v82
	v_exp_f32_e32 v83, v83
	v_add_f32_e32 v184, v80, v81
	v_mfma_f32_32x32x16_bf16 v[48:63], v[224:227], v[68:71], v[48:63]
	v_exp_f32_e32 v84, v84
	v_exp_f32_e32 v85, v85
	v_cvt_pk_bf16_f32 v72, v80, v81
	v_add_f32_e32 v185, v82, v83
	v_cvt_pk_bf16_f32 v73, v82, v83
	v_mfma_f32_32x32x16_bf16 v[16:31], v[234:237], v[68:71], v[16:31]
	v_exp_f32_e32 v86, v86
	v_exp_f32_e32 v87, v87
	v_add_f32_e32 v186, v84, v85
	v_cvt_pk_bf16_f32 v74, v84, v85
	v_add_f32_e32 v184, v184, v185
	v_mfma_f32_32x32x16_bf16 v[0:15], v[238:241], v[68:71], v[0:15]
	v_add_f32_e32 v187, v86, v87
	v_cvt_pk_bf16_f32 v75, v86, v87
	v_add_f32_e32 v186, v186, v187
	v_add_f32_e32 v184, v184, v186
	v_add_f32_e32 v206, v206, v184
	ds_read_b128 v[220:223], v219 offset:16384
	ds_read_b128 v[224:227], v219 offset:20480
	ds_read_b128 v[234:237], v219 offset:24576
	ds_read_b128 v[238:241], v219 offset:28672
	s_waitcnt lgkmcnt(4)
	v_mfma_f32_32x32x16_bf16 v[32:47], v[242:245], v[72:75], v[32:47]
	v_exp_f32_e32 v88, v88
	v_exp_f32_e32 v89, v89
	v_exp_f32_e32 v90, v90
	v_exp_f32_e32 v91, v91
	v_add_f32_e32 v184, v88, v89
	v_mfma_f32_32x32x16_bf16 v[48:63], v[246:249], v[72:75], v[48:63]
	v_exp_f32_e32 v92, v92
	v_exp_f32_e32 v93, v93
	v_cvt_pk_bf16_f32 v76, v88, v89
	v_add_f32_e32 v185, v90, v91
	v_cvt_pk_bf16_f32 v77, v90, v91
	v_mfma_f32_32x32x16_bf16 v[16:31], v[250:253], v[72:75], v[16:31]
	v_exp_f32_e32 v94, v94
	v_exp_f32_e32 v95, v95
	v_add_f32_e32 v186, v92, v93
	v_cvt_pk_bf16_f32 v78, v92, v93
	v_add_f32_e32 v184, v184, v185
	v_mfma_f32_32x32x16_bf16 v[0:15], v[200:203], v[72:75], v[0:15]
	v_add_f32_e32 v187, v94, v95
	v_cvt_pk_bf16_f32 v79, v94, v95
	v_add_f32_e32 v186, v186, v187
	v_add_f32_e32 v184, v184, v186
	v_add_f32_e32 v206, v206, v184
	s_waitcnt lgkmcnt(0)
	v_mfma_f32_32x32x16_bf16 v[32:47], v[220:223], v[76:79], v[32:47]
	v_mfma_f32_32x32x16_bf16 v[48:63], v[224:227], v[76:79], v[48:63]
	s_waitcnt lgkmcnt(0)
	s_barrier
	s_add_i32 s65, s65, 0x8000
	s_addk_i32 s23, 0x100
	s_add_i32 s36, s36, 64
	s_mov_b32 s33, s54
	s_cmpk_eq_i32 s23, 0x1e00
	v_mfma_f32_32x32x16_bf16 v[16:31], v[234:237], v[76:79], v[16:31]
	v_mfma_f32_32x32x16_bf16 v[0:15], v[238:241], v[76:79], v[0:15]
	s_setprio 0
	s_cbranch_scc0 .LqT_top
	s_branch .LBB0_284
